# c3sp + static s_setprio 1 for waves 4-7 during P5 indexer/select section (reset before attention)
# baseline (speedup 1.0000x reference)
; __device__ __forceinline__ void phase_attn(const Params& P, unsigned char* lds) {
;     ...
;     for (int idx = blockIdx.x; idx < 512; idx += gridDim.x) {
;         const int b = idx & 7; const int j = idx < 256 ? 63 - (idx >> 3) : ((idx - 256) >> 3);
;         const int s0 = j * 32, ntiles = j + 2;
;         for (int pp = 0; pp < 2; ++pp) {
;             const int p = wave * 2 + pp; const int sq = s0 + 2 * p + hh; const int rowq = b * SEQ + sq;
.LBB0_620:
	s_cmp_eq_u32 s101, 1
	s_cbranch_scc0 .Lsp_idx
	s_setprio 1

; __device__ __forceinline__ void phase_attn(const Params& P, unsigned char* lds) {
;     ...
;         __syncthreads();
;         {
;             const int g = wave >> 2;
;             bf16x8 Qf[8];
;             { const bf16_t* qp = Z1 + (size_t)(b * SEQ + s0 + lr) * LDZ + wave * 128 + hh * 8;
; #pragma unroll
;               for (int kk = 0; kk < 8; ++kk) Qf[kk] = *(const bf16x8*)(qp + kk * 16); }
; #pragma unroll
;             for (int kk = 0; kk < 8; ++kk) asm volatile("" :: "v"(Qf[kk]));
;             f32x16 o[4];
; #pragma unroll
;             for (int d = 0; d < 4; ++d)
; #pragma unroll
;                 for (int i = 0; i < 16; ++i) o[d][i] = 0.f;
;             float m = -1e30f, l = 0.f;
;             const int kkey0 = tid >> 5, kch = tid & 31;
;             const int vrow0 = tid >> 2, vc4 = tid & 3;
;             u32x4 sKa[2], sVa[2], sKb[2], sVb[2];
;     ...
;             auto tile_body = [&](const int tile, const int buf) __attribute__((always_inline)) {
;                 f32x16 S;
; #pragma unroll
;                 for (int i = 0; i < 16; ++i) S[i] = 0.f;
;                 const unsigned char* kb = lds + ATT_K_OFF + buf * 16384 + lr * 512 + g * 256;
; #pragma unroll
;                 for (int kk = 0; kk < 8; ++kk) { const bf16x8 Kf = *(const bf16x8*)(kb + (((2 * kk + hh) ^ (lr & 15)) * 16)); S = __builtin_amdgcn_mfma_f32_32x32x16_bf16(Kf, Qf[kk], S, 0, 0, 0); }
;                 const unsigned bits2 = bm[lr * 65 + tile] >> (4 * hh);
;                 float mx = S[0];
; #pragma unroll
;                 for (int i = 1; i < 16; ++i) mx = __builtin_fmaxf(mx, S[i]);
;                 mx *= 0.12751743f;
;                 mx = __builtin_fmaxf(mx, __shfl_xor(mx, 32));
;                 if (__any(mx > m)) { const float mn = __builtin_fmaxf(m, mx), al = __builtin_amdgcn_exp2f(m - mn);
; #pragma unroll
;                     for (int d = 0; d < 4; ++d)
; #pragma unroll
;                         for (int i = 0; i < 16; ++i) o[d][i] *= al;
;                     l *= al; m = mn; }
;                 float pr[16];
; #pragma unroll
;                 for (int i = 0; i < 16; ++i) { const int mk = __builtin_amdgcn_sbfe((int)bits2, (i & 3) + 8 * (i >> 2), 1);
;                     const float e = __builtin_amdgcn_exp2f(__builtin_fmaf(S[i], 0.12751743f, -m));
;                     pr[i] = __int_as_float(__float_as_int(e) & mk); l += pr[i]; }
;                 bf16x8 Pf[2];
.LBB0_816:
	s_setprio 0
	s_add_i32 s75, s75, s73
	v_or_b32_e32 v160, s75, v163
	v_mad_u64_u32 v[2:3], s[0:1], v160, s34, v[170:171]
	s_waitcnt lgkmcnt(0)
	s_barrier
	global_load_dwordx4 v[96:99], v[2:3], off
	global_load_dwordx4 v[100:103], v[2:3], off offset:32
	global_load_dwordx4 v[104:107], v[2:3], off offset:64
	global_load_dwordx4 v[108:111], v[2:3], off offset:96
	global_load_dwordx4 v[112:115], v[2:3], off offset:128
	global_load_dwordx4 v[116:119], v[2:3], off offset:160
	global_load_dwordx4 v[120:123], v[2:3], off offset:192
	global_load_dwordx4 v[124:127], v[2:3], off offset:224
	s_mulk_i32 s74, 0x4100
	v_or_b32_e32 v0, s74, v202
	v_or_b32_e32 v3, s73, v169
	v_lshlrev_b32_e32 v0, 6, v0
	v_or_b32_e32 v10, s73, v206
	v_lshl_add_u64 v[4:5], v[172:173], 0, v[0:1]
	v_mul_u32_u24_e32 v0, 0x1600, v3
	s_add_i32 s10, s73, -16
	v_lshl_add_u64 v[6:7], v[178:179], 0, v[0:1]
	v_mul_u32_u24_e32 v0, 0x1600, v10
	v_mov_b32_e32 v183, v1
	v_add_u32_e32 v2, s10, v169
	v_add_co_u32_e32 v8, vcc, s22, v4
	v_lshl_add_u64 v[10:11], s[44:45], 0, v[0:1]
	s_mov_b32 s0, 0x16000
	v_cndmask_b32_e64 v2, v2, v209, s[4:5]
	v_addc_co_u32_e32 v9, vcc, 0, v5, vcc
	v_lshl_add_u64 v[10:11], v[10:11], 0, v[182:183]
	v_mul_i32_i24_e32 v2, 0x1600, v2
	v_add_lshl_u32 v0, v207, s74, 6
	v_add_co_u32_e32 v14, vcc, s0, v10
	v_ashrrev_i32_e32 v3, 31, v2
	v_lshl_add_u64 v[12:13], v[172:173], 0, v[0:1]
	v_addc_co_u32_e32 v15, vcc, 0, v11, vcc
	v_lshl_add_u64 v[2:3], v[178:179], 0, v[2:3]
	v_add_co_u32_e32 v16, vcc, s22, v12
	s_and_b32 s0, s70, 7
	s_nop 0
	v_addc_co_u32_e32 v17, vcc, 0, v13, vcc
	v_mov_b32_e32 v0, v1
	v_mov_b32_e32 v161, v1
	v_mov_b32_e32 v188, 0xf149f2ca
	v_mov_b32_e32 v183, 0
	s_mov_b32 s11, 3
	v_mov_b32_e32 v186, v212
	v_mov_b32_e32 v187, v211
	v_mad_u64_u32 v[184:185], s[0:1], s0, v214, v[180:181]
	global_load_dwordx4 v[128:131], v[2:3], off offset:2048
	global_load_dwordx4 v[136:139], v[4:5], off
	global_load_dwordx4 v[144:147], v[6:7], off offset:2048
	global_load_dwordx4 v[152:155], v[8:9], off
	global_load_dwordx4 v[132:135], v[10:11], off offset:2048
	global_load_dwordx4 v[140:143], v[12:13], off
	global_load_dwordx4 v[148:151], v[14:15], off offset:2048
	global_load_dwordx4 v[156:159], v[16:17], off
	v_mov_b32_e32 v14, v1
	v_mov_b32_e32 v15, v1
	v_mov_b32_e32 v2, v1
	v_mov_b32_e32 v3, v1
	v_mov_b32_e32 v4, v1
	v_mov_b32_e32 v5, v1
	v_mov_b32_e32 v6, v1
	v_mov_b32_e32 v7, v1
	v_mov_b32_e32 v8, v1
	v_mov_b32_e32 v9, v1
	v_mov_b32_e32 v10, v1
	v_mov_b32_e32 v11, v1
	v_mov_b32_e32 v12, v1
	v_mov_b32_e32 v13, v1
	v_mov_b64_e32 v[30:31], v[14:15]
	v_mov_b64_e32 v[46:47], v[14:15]
	v_mov_b64_e32 v[62:63], v[14:15]
	v_mov_b64_e32 v[78:79], v[14:15]
	v_mov_b64_e32 v[28:29], v[12:13]
	v_mov_b64_e32 v[26:27], v[10:11]
	v_mov_b64_e32 v[24:25], v[8:9]
	v_mov_b64_e32 v[22:23], v[6:7]
	v_mov_b64_e32 v[20:21], v[4:5]
	v_mov_b64_e32 v[18:19], v[2:3]
	v_mov_b64_e32 v[16:17], v[0:1]
	v_mov_b64_e32 v[44:45], v[12:13]
	v_mov_b64_e32 v[42:43], v[10:11]
	v_mov_b64_e32 v[40:41], v[8:9]
	v_mov_b64_e32 v[38:39], v[6:7]
	v_mov_b64_e32 v[36:37], v[4:5]
	v_mov_b64_e32 v[34:35], v[2:3]
	v_mov_b64_e32 v[32:33], v[0:1]
	v_mov_b64_e32 v[60:61], v[12:13]
	v_mov_b64_e32 v[58:59], v[10:11]
	v_mov_b64_e32 v[56:57], v[8:9]
	v_mov_b64_e32 v[54:55], v[6:7]
	v_mov_b64_e32 v[52:53], v[4:5]
	v_mov_b64_e32 v[50:51], v[2:3]
	v_mov_b64_e32 v[48:49], v[0:1]
	v_mov_b64_e32 v[76:77], v[12:13]
	v_mov_b64_e32 v[74:75], v[10:11]
	v_mov_b64_e32 v[72:73], v[8:9]
	v_mov_b64_e32 v[70:71], v[6:7]
	v_mov_b64_e32 v[68:69], v[4:5]
	v_mov_b64_e32 v[66:67], v[2:3]
	v_mov_b64_e32 v[64:65], v[0:1]
	s_waitcnt vmcnt(7)
	ds_write_b128 v215, v[128:131]
	s_waitcnt vmcnt(6)
	ds_write_b128 v216, v[136:139] offset:32768
	s_waitcnt vmcnt(5)
	ds_write_b128 v215, v[144:147] offset:8192
	s_waitcnt vmcnt(4)
	ds_write_b128 v216, v[152:155] offset:43008
	s_waitcnt lgkmcnt(0)
	s_barrier
	s_branch .LBB0_818
